# SGU unit: weight staging loads batched (one wait instead of four round trips) and gate-row loads issued before the normalise stage
# speedup vs baseline: 1.0049x; 1.0049x over previous
.LBB0_776:
	s_or_b64 exec, exec, s[4:5]
	s_waitcnt vmcnt(0)
	ds_write_b128 v116, v[100:103] offset:34816
	ds_write_b128 v118, v[104:107] offset:34816
	ds_write_b128 v120, v[108:111] offset:34816
	ds_write_b128 v122, v[112:115] offset:34816
.LBB0_777:
	v_ashrrev_i32_e32 v52, 2, v52
	v_add_u32_e32 v2, s12, v52
	v_ashrrev_i32_e32 v3, 31, v2
	v_lshlrev_b32_e32 v0, 5, v51
	v_lshlrev_b64 v[2:3], 12, v[2:3]
	v_and_b32_e32 v14, 0x60, v0
	v_lshl_add_u64 v[2:3], s[2:3], 0, v[2:3]
	s_lshl_b32 s68, s13, 8
	v_and_or_b32 v124, v52, -16, v50
	v_add_u32_e32 v124, s12, v124
	v_ashrrev_i32_e32 v125, 31, v124
	v_lshlrev_b64 v[124:125], 12, v[124:125]
	v_lshl_add_u64 v[124:125], s[2:3], 0, v[124:125]
	v_lshl_add_u64 v[124:125], v[124:125], 0, s[68:69]
	v_lshrrev_b32_e32 v126, 1, v51
	v_and_b32_e32 v126, 24, v126
	v_mov_b32_e32 v127, 0
	v_lshl_add_u64 v[124:125], v[124:125], 0, v[126:127]
	global_load_dwordx2 v[130:131], v[124:125], off offset:2048
	global_load_dwordx2 v[132:133], v[124:125], off offset:2080
	global_load_dwordx2 v[134:135], v[124:125], off offset:2112
	global_load_dwordx2 v[136:137], v[124:125], off offset:2144
	global_load_dwordx2 v[138:139], v[124:125], off offset:2176
	global_load_dwordx2 v[140:141], v[124:125], off offset:2208
	global_load_dwordx2 v[142:143], v[124:125], off offset:2240
	global_load_dwordx2 v[144:145], v[124:125], off offset:2272
	v_lshl_add_u64 v[2:3], v[2:3], 0, s[68:69]
	v_lshlrev_b32_e32 v0, 1, v14
	s_waitcnt lgkmcnt(0)
	v_lshl_add_u64 v[4:5], v[2:3], 0, v[0:1]
	s_barrier
	global_load_dwordx4 v[6:9], v[4:5], off offset:3072
	global_load_dwordx4 v[10:13], v[4:5], off offset:3088
	v_lshl_add_u32 v0, v52, 3, 0
	s_add_i32 s4, 0, 0x11400
	v_add_u32_e32 v0, 0x11000, v0
	v_lshlrev_b32_e32 v15, 2, v14
	v_mul_u32_u24_e32 v14, 0x88, v14
	v_lshlrev_b32_e32 v22, 1, v52
	ds_read_b64 v[2:3], v0
	v_add_u32_e32 v0, s4, v15
	v_add_u32_e32 v15, 0, v15
	v_lshlrev_b32_e32 v23, 1, v14
	v_add_u32_e32 v53, 0x11600, v15
	ds_read2_b64 v[14:17], v0 offset1:1
	ds_read2_b64 v[18:21], v0 offset0:2 offset1:3
	v_add3_u32 v54, 0, v22, v23
	v_add3_u32 v55, 0, v23, v22
	ds_read2_b64 v[22:25], v0 offset0:4 offset1:5
	ds_read2_b64 v[26:29], v0 offset0:6 offset1:7
	ds_read2_b64 v[30:33], v53 offset1:1
	ds_read2_b64 v[34:37], v53 offset0:2 offset1:3
	ds_read2_b64 v[38:41], v53 offset0:4 offset1:5
	ds_read2_b64 v[42:45], v53 offset0:6 offset1:7
	global_load_dwordx4 v[46:49], v[4:5], off offset:3104
	s_add_i32 s10, s10, s11
	s_cmpk_lt_i32 s10, 0x180
	s_mov_b32 s6, s13
	s_waitcnt vmcnt(2)
	v_lshlrev_b32_e32 v56, 16, v6
	v_and_b32_e32 v6, 0xffff0000, v6
	v_lshlrev_b32_e32 v57, 16, v7
	v_and_b32_e32 v7, 0xffff0000, v7
	v_lshlrev_b32_e32 v58, 16, v8
	v_and_b32_e32 v8, 0xffff0000, v8
	v_lshlrev_b32_e32 v59, 16, v9
	s_waitcnt lgkmcnt(8)
	v_sub_f32_e32 v56, v56, v2
	v_sub_f32_e32 v6, v6, v2
	v_and_b32_e32 v9, 0xffff0000, v9
	s_waitcnt vmcnt(1)
	v_lshlrev_b32_e32 v60, 16, v10
	v_and_b32_e32 v10, 0xffff0000, v10
	v_sub_f32_e32 v57, v57, v2
	v_sub_f32_e32 v7, v7, v2
	v_sub_f32_e32 v58, v58, v2
	v_sub_f32_e32 v8, v8, v2
	v_sub_f32_e32 v59, v59, v2
	v_mul_f32_e32 v56, v3, v56
	v_mul_f32_e32 v6, v3, v6
	v_sub_f32_e32 v9, v9, v2
	v_sub_f32_e32 v10, v10, v2
	v_mul_f32_e32 v57, v3, v57
	v_mul_f32_e32 v7, v3, v7
	v_mul_f32_e32 v58, v3, v58
	v_mul_f32_e32 v8, v3, v8
	v_mul_f32_e32 v59, v3, v59
	s_waitcnt lgkmcnt(3)
	v_fma_f32 v14, v14, v56, v30
	v_fma_f32 v6, v15, v6, v31
	v_mul_f32_e32 v9, v3, v9
	v_mul_f32_e32 v10, v3, v10
	v_fma_f32 v15, v57, v16, v32
	v_fmac_f32_e32 v33, v7, v17
	s_waitcnt lgkmcnt(2)
	v_fma_f32 v7, v58, v18, v34
	v_fma_f32 v8, v8, v19, v35
	v_fma_f32 v16, v59, v20, v36
	v_cvt_pk_bf16_f32 v14, v14, v1
	v_cvt_pk_bf16_f32 v6, v6, v1
	v_sub_f32_e32 v60, v60, v2
	v_fmac_f32_e32 v37, v9, v21
	v_cvt_pk_bf16_f32 v15, v15, v1
	v_cvt_pk_bf16_f32 v17, v33, v1
	v_cvt_pk_bf16_f32 v7, v7, v1
	v_cvt_pk_bf16_f32 v8, v8, v1
	v_cvt_pk_bf16_f32 v16, v16, v1
	v_cvt_pk_bf16_f32 v18, v37, v1
	ds_write_b16 v54, v14
	ds_write_b16 v55, v6 offset:272
	ds_write_b16 v54, v15 offset:544
	ds_write_b16 v55, v17 offset:816
	ds_write_b16 v54, v7 offset:1088
	ds_write_b16 v55, v8 offset:1360
	ds_write_b16 v54, v16 offset:1632
	ds_write_b16 v55, v18 offset:1904
	s_waitcnt lgkmcnt(9)
	v_fma_f32 v6, v23, v10, v39
	v_mul_f32_e32 v60, v3, v60
	v_cvt_pk_bf16_f32 v6, v6, v1
	v_fma_f32 v9, v22, v60, v38
	v_cvt_pk_bf16_f32 v7, v9, v1
	ds_write_b16 v55, v6 offset:2448
	v_lshlrev_b32_e32 v6, 16, v11
	ds_write_b16 v54, v7 offset:2176
	v_sub_f32_e32 v6, v6, v2
	v_and_b32_e32 v7, 0xffff0000, v11
	v_mul_f32_e32 v6, v3, v6
	v_sub_f32_e32 v7, v7, v2
	v_fma_f32 v6, v6, v24, v40
	v_mul_f32_e32 v7, v3, v7
	v_fmac_f32_e32 v41, v7, v25
	v_cvt_pk_bf16_f32 v8, v6, v1
	global_load_dwordx4 v[4:7], v[4:5], off offset:3120
	ds_write_b16 v54, v8 offset:2720
	v_cvt_pk_bf16_f32 v8, v41, v1
	ds_write_b16 v55, v8 offset:2992
	v_lshlrev_b32_e32 v8, 16, v12
	v_sub_f32_e32 v8, v8, v2
	v_mul_f32_e32 v8, v3, v8
	v_and_b32_e32 v9, 0xffff0000, v12
	s_waitcnt lgkmcnt(12)
	v_fma_f32 v8, v8, v26, v42
	v_sub_f32_e32 v9, v9, v2
	v_mul_f32_e32 v9, v3, v9
	v_cvt_pk_bf16_f32 v8, v8, v1
	v_fma_f32 v9, v9, v27, v43
	ds_write_b16 v54, v8 offset:3264
	v_cvt_pk_bf16_f32 v8, v9, v1
	ds_write_b16 v55, v8 offset:3536
	v_lshlrev_b32_e32 v8, 16, v13
	v_sub_f32_e32 v8, v8, v2
	v_mul_f32_e32 v8, v3, v8
	v_and_b32_e32 v9, 0xffff0000, v13
	v_fma_f32 v8, v8, v28, v44
	v_sub_f32_e32 v9, v9, v2
	v_mul_f32_e32 v9, v3, v9
	v_cvt_pk_bf16_f32 v8, v8, v1
	v_fmac_f32_e32 v45, v9, v29
	ds_write_b16 v54, v8 offset:3808
	v_cvt_pk_bf16_f32 v8, v45, v1
	ds_write_b16 v55, v8 offset:4080
	ds_read2_b64 v[8:11], v0 offset0:8 offset1:9
	ds_read2_b64 v[12:15], v53 offset0:8 offset1:9
	s_waitcnt vmcnt(1)
	v_lshlrev_b32_e32 v16, 16, v46
	v_sub_f32_e32 v16, v16, v2
	v_mul_f32_e32 v24, v3, v16
	ds_read2_b64 v[16:19], v0 offset0:10 offset1:11
	ds_read2_b64 v[20:23], v53 offset0:10 offset1:11
	s_waitcnt lgkmcnt(2)
	v_fma_f32 v8, v8, v24, v12
	v_and_b32_e32 v12, 0xffff0000, v46
	v_sub_f32_e32 v12, v12, v2
	v_mul_f32_e32 v12, v3, v12
	v_cvt_pk_bf16_f32 v8, v8, v1
	v_fma_f32 v9, v9, v12, v13
	ds_write_b16 v54, v8 offset:4352
	v_cvt_pk_bf16_f32 v8, v9, v1
	ds_write_b16 v55, v8 offset:4624
	v_lshlrev_b32_e32 v8, 16, v47
	v_sub_f32_e32 v8, v8, v2
	v_mul_f32_e32 v8, v3, v8
	v_and_b32_e32 v9, 0xffff0000, v47
	v_fma_f32 v8, v8, v10, v14
	v_sub_f32_e32 v9, v9, v2
	v_mul_f32_e32 v9, v3, v9
	v_cvt_pk_bf16_f32 v8, v8, v1
	v_fmac_f32_e32 v15, v9, v11
	ds_write_b16 v54, v8 offset:4896
	v_cvt_pk_bf16_f32 v8, v15, v1
	ds_write_b16 v55, v8 offset:5168
	v_lshlrev_b32_e32 v8, 16, v48
	v_sub_f32_e32 v8, v8, v2
	v_mul_f32_e32 v8, v3, v8
	v_and_b32_e32 v9, 0xffff0000, v48
	s_waitcnt lgkmcnt(4)
	v_fma_f32 v8, v8, v16, v20
	v_sub_f32_e32 v9, v9, v2
	v_mul_f32_e32 v9, v3, v9
	v_cvt_pk_bf16_f32 v8, v8, v1
	v_fma_f32 v9, v9, v17, v21
	ds_write_b16 v54, v8 offset:5440
	v_cvt_pk_bf16_f32 v8, v9, v1
	ds_write_b16 v55, v8 offset:5712
	v_lshlrev_b32_e32 v8, 16, v49
	v_sub_f32_e32 v8, v8, v2
	v_mul_f32_e32 v8, v3, v8
	v_and_b32_e32 v9, 0xffff0000, v49
	v_fma_f32 v8, v8, v18, v22
	v_sub_f32_e32 v9, v9, v2
	v_mul_f32_e32 v9, v3, v9
	v_cvt_pk_bf16_f32 v8, v8, v1
	v_fmac_f32_e32 v23, v9, v19
	ds_write_b16 v54, v8 offset:5984
	v_cvt_pk_bf16_f32 v8, v23, v1
	ds_write_b16 v55, v8 offset:6256
	ds_read2_b64 v[8:11], v0 offset0:12 offset1:13
	ds_read2_b64 v[12:15], v53 offset0:12 offset1:13
	s_waitcnt vmcnt(0)
	v_lshlrev_b32_e32 v16, 16, v4
	v_sub_f32_e32 v16, v16, v2
	v_mul_f32_e32 v24, v3, v16
	v_and_b32_e32 v4, 0xffff0000, v4
	ds_read2_b64 v[16:19], v0 offset0:14 offset1:15
	ds_read2_b64 v[20:23], v53 offset0:14 offset1:15
	s_waitcnt lgkmcnt(2)
	v_fma_f32 v0, v8, v24, v12
	v_sub_f32_e32 v4, v4, v2
	v_mul_f32_e32 v4, v3, v4
	v_cvt_pk_bf16_f32 v0, v0, v1
	v_fma_f32 v4, v9, v4, v13
	ds_write_b16 v54, v0 offset:6528
	v_cvt_pk_bf16_f32 v0, v4, v1
	ds_write_b16 v55, v0 offset:6800
	v_lshlrev_b32_e32 v0, 16, v5
	v_sub_f32_e32 v0, v0, v2
	v_mul_f32_e32 v0, v3, v0
	v_and_b32_e32 v4, 0xffff0000, v5
	v_fma_f32 v0, v0, v10, v14
	v_sub_f32_e32 v4, v4, v2
	v_mul_f32_e32 v4, v3, v4
	v_cvt_pk_bf16_f32 v0, v0, v1
	v_fmac_f32_e32 v15, v4, v11
	ds_write_b16 v54, v0 offset:7072
	v_cvt_pk_bf16_f32 v0, v15, v1
	ds_write_b16 v55, v0 offset:7344
	v_lshlrev_b32_e32 v0, 16, v6
	v_sub_f32_e32 v0, v0, v2
	v_mul_f32_e32 v0, v3, v0
	v_and_b32_e32 v4, 0xffff0000, v6
	s_waitcnt lgkmcnt(4)
	v_fma_f32 v0, v0, v16, v20
	v_sub_f32_e32 v4, v4, v2
	v_mul_f32_e32 v4, v3, v4
	v_cvt_pk_bf16_f32 v0, v0, v1
	v_fma_f32 v4, v4, v17, v21
	ds_write_b16 v54, v0 offset:7616
	v_cvt_pk_bf16_f32 v0, v4, v1
	ds_write_b16 v55, v0 offset:7888
	v_lshlrev_b32_e32 v0, 16, v7
	v_sub_f32_e32 v0, v0, v2
	v_mul_f32_e32 v0, v3, v0
	v_and_b32_e32 v4, 0xffff0000, v7
	v_and_or_b32 v20, v52, -16, v50
	v_fma_f32 v0, v0, v18, v22
	v_sub_f32_e32 v2, v4, v2
	v_add_u32_e32 v32, s12, v20
	v_mul_f32_e32 v2, v3, v2
	v_cvt_pk_bf16_f32 v0, v0, v1
	v_ashrrev_i32_e32 v33, 31, v32
	v_fmac_f32_e32 v23, v2, v19
	ds_write_b16 v54, v0 offset:8160
	v_cvt_pk_bf16_f32 v0, v23, v1
	v_lshlrev_b64 v[2:3], 12, v[32:33]
	ds_write_b16 v55, v0 offset:8432
	v_lshl_add_u64 v[2:3], s[2:3], 0, v[2:3]
	v_lshrrev_b32_e32 v0, 1, v51
	v_lshl_add_u64 v[2:3], v[2:3], 0, s[68:69]
	v_and_b32_e32 v0, 24, v0
	v_lshl_add_u64 v[18:19], v[2:3], 0, v[0:1]
	s_waitcnt lgkmcnt(0)
	s_barrier
	s_nop 0
	v_mov_b64_e32 v[36:37], v[130:131]
	s_nop 0
	v_mov_b64_e32 v[42:43], v[132:133]
	v_and_b32_e32 v2, 48, v51
	s_nop 0
	v_mov_b64_e32 v[44:45], v[134:135]
	v_add_u32_e32 v2, 0, v2
	s_movk_i32 s2, 0x110
	v_mad_u32_u24 v50, v50, s2, v2
	ds_read_b128 v[10:13], v50
	v_mad_u64_u32 v[34:35], s[2:3], v20, s2, v[2:3]
	ds_read_b128 v[14:17], v50 offset:64
	ds_read_b128 v[6:9], v34 offset:34816
	ds_read_b128 v[2:5], v34 offset:34880
	s_waitcnt lgkmcnt(1)
	v_mfma_f32_16x16x32_bf16 v[10:13], v[10:13], v[6:9], 0
	v_lshl_add_u32 v20, v20, 2, s4
	ds_read_b32 v51, v20 offset:1024
	ds_read_b128 v[20:23], v50 offset:128
	ds_read_b128 v[24:27], v50 offset:192
	s_waitcnt lgkmcnt(3)
	v_mfma_f32_16x16x32_bf16 v[28:31], v[14:17], v[2:5], v[10:13]
	ds_read_b128 v[14:17], v34 offset:34944
	s_nop 1
	ds_read_b128 v[10:13], v34 offset:35008
	s_nop 0
	v_mov_b64_e32 v[46:47], v[136:137]
	v_lshlrev_b64 v[32:33], 11, v[32:33]
	s_waitcnt lgkmcnt(1)
	v_mfma_f32_16x16x32_bf16 v[20:23], v[20:23], v[14:17], v[28:31]
	v_and_b32_e32 v53, 0xffff0000, v37
	s_waitcnt lgkmcnt(0)
	v_mfma_f32_16x16x32_bf16 v[20:23], v[24:27], v[10:13], v[20:23]
	v_lshl_add_u64 v[28:29], s[0:1], 0, v[32:33]
	v_lshl_add_u64 v[40:41], v[28:29], 0, s[68:69]
	ds_read_b128 v[28:31], v50 offset:4352
	v_lshlrev_b32_e32 v24, 16, v36
	ds_read_b128 v[32:35], v50 offset:4480
	s_nop 2
	v_add_f32_e32 v20, v51, v20
	v_mul_f32_e32 v20, v20, v24
	v_add_f32_e32 v21, v51, v21
	v_and_b32_e32 v24, 0xffff0000, v36
	v_mul_f32_e32 v21, v21, v24
	ds_read_b128 v[24:27], v50 offset:4416
	s_waitcnt lgkmcnt(2)
	v_mfma_f32_16x16x32_bf16 v[28:31], v[28:31], v[6:9], 0
	v_cvt_pk_bf16_f32 v48, v20, v21
	v_add_f32_e32 v20, v51, v22
	v_lshlrev_b32_e32 v21, 16, v37
	v_mul_f32_e32 v49, v20, v21
	v_add_f32_e32 v52, v51, v23
	s_waitcnt lgkmcnt(0)
	v_mfma_f32_16x16x32_bf16 v[20:23], v[24:27], v[2:5], v[28:31]
	ds_read_b128 v[36:39], v50 offset:4544
	v_mul_f32_e32 v24, v52, v53
	v_lshl_add_u64 v[26:27], v[40:41], 0, v[0:1]
	s_mov_b64 s[0:1], 0xce84100
	v_cvt_pk_bf16_f32 v49, v49, v24
	v_mfma_f32_16x16x32_bf16 v[22:25], v[32:35], v[14:17], v[20:23]
	ds_read_b128 v[30:33], v50 offset:8768
	v_readlane_b32 s68, v254, 63
	s_nop 0
	v_lshl_add_u64 v[20:21], v[26:27], 0, s[0:1]
	global_store_dwordx2 v[20:21], v[48:49], off offset:1024
	s_nop 0
	v_mov_b64_e32 v[48:49], v[138:139]
	ds_read_b128 v[26:29], v50 offset:8704
	s_waitcnt lgkmcnt(2)
	v_mfma_f32_16x16x32_bf16 v[22:25], v[36:39], v[10:13], v[22:25]
	ds_read_b128 v[34:37], v50 offset:8832
	ds_read_b128 v[38:41], v50 offset:8896
	s_waitcnt lgkmcnt(2)
	v_mfma_f32_16x16x32_bf16 v[26:29], v[26:29], v[6:9], 0
	s_nop 3
	v_add_f32_e32 v0, v51, v22
	v_lshlrev_b32_e32 v22, 16, v42
	v_mul_f32_e32 v0, v0, v22
	v_add_f32_e32 v22, v51, v23
	v_and_b32_e32 v23, 0xffff0000, v42
	v_mul_f32_e32 v22, v22, v23
	v_cvt_pk_bf16_f32 v42, v0, v22
	v_add_f32_e32 v0, v51, v24
	v_lshlrev_b32_e32 v22, 16, v43
	v_mul_f32_e32 v0, v0, v22
	v_add_f32_e32 v22, v51, v25
	v_and_b32_e32 v23, 0xffff0000, v43
	v_mfma_f32_16x16x32_bf16 v[26:29], v[30:33], v[2:5], v[26:29]
	v_mul_f32_e32 v30, v22, v23
	v_cvt_pk_bf16_f32 v43, v0, v30
	global_store_dwordx2 v[20:21], v[42:43], off offset:1056
	s_nop 0
	v_mov_b64_e32 v[42:43], v[140:141]
	s_waitcnt lgkmcnt(1)
	v_mfma_f32_16x16x32_bf16 v[22:25], v[34:37], v[14:17], v[26:29]
	ds_read_b128 v[30:33], v50 offset:13120
	ds_read_b128 v[34:37], v50 offset:13184
	s_nop 0
	ds_read_b128 v[26:29], v50 offset:13056
	s_waitcnt lgkmcnt(3)
	v_mfma_f32_16x16x32_bf16 v[22:25], v[38:41], v[10:13], v[22:25]
	ds_read_b128 v[38:41], v50 offset:13248
	s_waitcnt lgkmcnt(1)
	v_mfma_f32_16x16x32_bf16 v[26:29], v[26:29], v[6:9], 0
	s_nop 4
	v_add_f32_e32 v0, v51, v22
	v_lshlrev_b32_e32 v22, 16, v44
	v_mul_f32_e32 v0, v0, v22
	v_add_f32_e32 v22, v51, v23
	v_and_b32_e32 v23, 0xffff0000, v44
	v_mul_f32_e32 v22, v22, v23
	v_cvt_pk_bf16_f32 v44, v0, v22
	v_add_f32_e32 v0, v51, v24
	v_lshlrev_b32_e32 v22, 16, v45
	v_mul_f32_e32 v0, v0, v22
	v_add_f32_e32 v22, v51, v25
	v_and_b32_e32 v23, 0xffff0000, v45
	v_mfma_f32_16x16x32_bf16 v[26:29], v[30:33], v[2:5], v[26:29]
	v_mul_f32_e32 v30, v22, v23
	v_cvt_pk_bf16_f32 v45, v0, v30
	global_store_dwordx2 v[20:21], v[44:45], off offset:1088
	s_nop 0
	v_mov_b64_e32 v[44:45], v[142:143]
	v_mfma_f32_16x16x32_bf16 v[22:25], v[34:37], v[14:17], v[26:29]
	s_nop 0
	v_mov_b64_e32 v[18:19], v[144:145]
	ds_read_b128 v[30:33], v50 offset:17472
	ds_read_b128 v[34:37], v50 offset:17536
	s_nop 0
	ds_read_b128 v[26:29], v50 offset:17408
	s_waitcnt lgkmcnt(3)
	v_mfma_f32_16x16x32_bf16 v[22:25], v[38:41], v[10:13], v[22:25]
	s_waitcnt lgkmcnt(0)
	v_mfma_f32_16x16x32_bf16 v[26:29], v[26:29], v[6:9], 0
	s_nop 5
	v_add_f32_e32 v0, v51, v22
	v_lshlrev_b32_e32 v22, 16, v46
	v_mul_f32_e32 v0, v0, v22
	v_add_f32_e32 v22, v51, v23
	v_and_b32_e32 v23, 0xffff0000, v46
	v_mul_f32_e32 v22, v22, v23
	v_cvt_pk_bf16_f32 v38, v0, v22
	v_add_f32_e32 v0, v51, v24
	v_lshlrev_b32_e32 v22, 16, v47
	v_mul_f32_e32 v0, v0, v22
	v_add_f32_e32 v39, v51, v25
	ds_read_b128 v[22:25], v50 offset:17600
	v_mfma_f32_16x16x32_bf16 v[26:29], v[30:33], v[2:5], v[26:29]
	v_and_b32_e32 v30, 0xffff0000, v47
	v_mul_f32_e32 v30, v39, v30
	v_cvt_pk_bf16_f32 v39, v0, v30
	v_mfma_f32_16x16x32_bf16 v[26:29], v[34:37], v[14:17], v[26:29]
	ds_read_b128 v[30:33], v50 offset:21760
	ds_read_b128 v[34:37], v50 offset:21888
	global_store_dwordx2 v[20:21], v[38:39], off offset:1120
	s_waitcnt lgkmcnt(2)
	v_mfma_f32_16x16x32_bf16 v[22:25], v[22:25], v[10:13], v[26:29]
	ds_read_b128 v[38:41], v50 offset:21952
	s_nop 1
	ds_read_b128 v[26:29], v50 offset:21824
	s_waitcnt lgkmcnt(3)
	v_mfma_f32_16x16x32_bf16 v[30:33], v[30:33], v[6:9], 0
	s_nop 1
	v_add_f32_e32 v0, v51, v22
	v_lshlrev_b32_e32 v22, 16, v48
	v_mul_f32_e32 v0, v0, v22
	v_add_f32_e32 v22, v51, v23
	v_and_b32_e32 v23, 0xffff0000, v48
	s_waitcnt lgkmcnt(0)
	v_mfma_f32_16x16x32_bf16 v[26:29], v[26:29], v[2:5], v[30:33]
	v_mul_f32_e32 v22, v22, v23
	v_cvt_pk_bf16_f32 v46, v0, v22
	v_add_f32_e32 v0, v51, v24
	v_lshlrev_b32_e32 v22, 16, v49
	v_mul_f32_e32 v0, v0, v22
	v_add_f32_e32 v22, v51, v25
	v_and_b32_e32 v23, 0xffff0000, v49
	v_mul_f32_e32 v30, v22, v23
	v_mfma_f32_16x16x32_bf16 v[22:25], v[34:37], v[14:17], v[26:29]
	v_cvt_pk_bf16_f32 v47, v0, v30
	ds_read_b128 v[30:33], v50 offset:26176
	ds_read_b128 v[34:37], v50 offset:26240
	v_mfma_f32_16x16x32_bf16 v[22:25], v[38:41], v[10:13], v[22:25]
	ds_read_b128 v[26:29], v50 offset:26112
	ds_read_b128 v[38:41], v50 offset:26304
	global_store_dwordx2 v[20:21], v[46:47], off offset:1152
	s_waitcnt lgkmcnt(1)
	v_mfma_f32_16x16x32_bf16 v[26:29], v[26:29], v[6:9], 0
	s_nop 2
	v_add_f32_e32 v0, v51, v22
	v_lshlrev_b32_e32 v22, 16, v42
	v_mul_f32_e32 v0, v0, v22
	v_add_f32_e32 v22, v51, v23
	v_and_b32_e32 v23, 0xffff0000, v42
	v_mfma_f32_16x16x32_bf16 v[26:29], v[30:33], v[2:5], v[26:29]
	v_mul_f32_e32 v22, v22, v23
	v_cvt_pk_bf16_f32 v42, v0, v22
	v_add_f32_e32 v0, v51, v24
	v_lshlrev_b32_e32 v22, 16, v43
	v_mul_f32_e32 v0, v0, v22
	v_add_f32_e32 v22, v51, v25
	v_and_b32_e32 v23, 0xffff0000, v43
	v_mul_f32_e32 v30, v22, v23
	v_mfma_f32_16x16x32_bf16 v[22:25], v[34:37], v[14:17], v[26:29]
	v_cvt_pk_bf16_f32 v43, v0, v30
	ds_read_b128 v[30:33], v50 offset:30528
	ds_read_b128 v[34:37], v50 offset:30592
	s_waitcnt lgkmcnt(2)
	v_mfma_f32_16x16x32_bf16 v[22:25], v[38:41], v[10:13], v[22:25]
	ds_read_b128 v[26:29], v50 offset:30464
	global_store_dwordx2 v[20:21], v[42:43], off offset:1184
	s_waitcnt lgkmcnt(0)
	v_mfma_f32_16x16x32_bf16 v[6:9], v[26:29], v[6:9], 0
	ds_read_b128 v[26:29], v50 offset:30656
	s_nop 2
	v_add_f32_e32 v0, v51, v22
	v_lshlrev_b32_e32 v22, 16, v44
	v_mfma_f32_16x16x32_bf16 v[2:5], v[30:33], v[2:5], v[6:9]
	v_mul_f32_e32 v0, v0, v22
	v_add_f32_e32 v22, v51, v23
	v_and_b32_e32 v23, 0xffff0000, v44
	v_mfma_f32_16x16x32_bf16 v[2:5], v[34:37], v[14:17], v[2:5]
	v_mul_f32_e32 v22, v22, v23
	v_cvt_pk_bf16_f32 v22, v0, v22
	v_add_f32_e32 v0, v51, v24
	s_waitcnt lgkmcnt(0)
	v_mfma_f32_16x16x32_bf16 v[2:5], v[26:29], v[10:13], v[2:5]
	v_lshlrev_b32_e32 v23, 16, v45
	v_mul_f32_e32 v0, v0, v23
	v_add_f32_e32 v6, v51, v25
	v_and_b32_e32 v7, 0xffff0000, v45
	v_mul_f32_e32 v6, v6, v7
	v_cvt_pk_bf16_f32 v23, v0, v6
	s_nop 2
	v_add_f32_e32 v0, v51, v2
	v_lshlrev_b32_e32 v2, 16, v18
	v_mul_f32_e32 v0, v0, v2
	v_add_f32_e32 v2, v51, v3
	v_and_b32_e32 v3, 0xffff0000, v18
	v_mul_f32_e32 v2, v2, v3
	v_cvt_pk_bf16_f32 v2, v0, v2
	v_add_f32_e32 v0, v51, v4
	v_lshlrev_b32_e32 v3, 16, v19
	v_mul_f32_e32 v0, v0, v3
	v_add_f32_e32 v3, v51, v5
	v_and_b32_e32 v4, 0xffff0000, v19
	v_mul_f32_e32 v3, v3, v4
	global_store_dwordx2 v[20:21], v[22:23], off offset:1216
	v_cvt_pk_bf16_f32 v3, v0, v3
	global_store_dwordx2 v[20:21], v[2:3], off offset:1248
	s_barrier
	s_cbranch_scc0 .LBB0_796

.LBB0_786:
	s_or_b64 exec, exec, s[4:5]
	s_bfe_u32 s13, s10, 0x20003
	s_cmp_eq_u32 s13, s6
	s_cbranch_scc1 .LBB0_777
	v_readlane_b32 s4, v254, 32
	s_or_b32 s14, s13, s4
	s_lshl_b32 s4, s14, 15
	v_lshlrev_b32_e32 v0, 3, v50
	s_add_u32 s4, s0, s4
	s_addc_u32 s5, s1, 0
	v_lshlrev_b32_e32 v0, 1, v0
	v_lshl_add_u64 v[2:3], s[4:5], 0, v[0:1]
	s_mov_b64 s[4:5], 0x5644100
	v_lshl_add_u64 v[6:7], v[2:3], 0, s[4:5]
	v_lshlrev_b32_e32 v2, 7, v53
	v_ashrrev_i32_e32 v3, 31, v2
	v_lshl_add_u64 v[2:3], v[2:3], 1, v[6:7]
	s_waitcnt lgkmcnt(0)
	global_load_dwordx4 v[100:103], v[2:3], off
	v_lshl_add_u32 v0, v50, 4, 0
	s_movk_i32 s6, 0x110
	v_mad_u64_u32 v[116:117], s[4:5], v53, s6, v[0:1]
	v_add_u32_e32 v2, 0x200, v52
	v_ashrrev_i32_e32 v8, 4, v2
	v_lshlrev_b32_e32 v2, 7, v8
	v_ashrrev_i32_e32 v3, 31, v2
	v_lshl_add_u64 v[2:3], v[2:3], 1, v[6:7]
	global_load_dwordx4 v[104:107], v[2:3], off
	v_mad_u64_u32 v[118:119], s[4:5], v8, s6, v[0:1]
	v_add_u32_e32 v2, 0x400, v52
	v_ashrrev_i32_e32 v8, 4, v2
	v_lshlrev_b32_e32 v2, 7, v8
	v_ashrrev_i32_e32 v3, 31, v2
	v_lshl_add_u64 v[2:3], v[2:3], 1, v[6:7]
	global_load_dwordx4 v[108:111], v[2:3], off
	v_mad_u64_u32 v[120:121], s[4:5], v8, s6, v[0:1]
	v_add_u32_e32 v2, 0x600, v52
	v_ashrrev_i32_e32 v8, 4, v2
	v_lshlrev_b32_e32 v2, 7, v8
	v_ashrrev_i32_e32 v3, 31, v2
	v_lshl_add_u64 v[2:3], v[2:3], 1, v[6:7]
	global_load_dwordx4 v[112:115], v[2:3], off
	v_mad_u64_u32 v[122:123], s[4:5], v8, s6, v[0:1]
	s_movk_i32 s4, 0x180
	s_nop 0
	v_cmp_gt_i32_e32 vcc, s4, v52
	s_and_saveexec_b64 s[4:5], vcc
	s_cbranch_execz .LBB0_776
	s_movk_i32 s6, 0x7f
	v_cmp_lt_u32_e32 vcc, s6, v52
	s_and_saveexec_b64 s[6:7], vcc
	s_xor_b64 s[6:7], exec, s[6:7]
	s_cbranch_execz .LBB0_794
	v_and_b32_e32 v0, 0xffffff80, v52
	s_movk_i32 s8, 0x80
	v_cmp_ne_u32_e32 vcc, s8, v0
	s_and_saveexec_b64 s[8:9], vcc
	s_xor_b64 s[8:9], exec, s[8:9]
	s_lshl_b32 s14, s14, 7
	s_add_i32 s15, s14, 0x3400
	s_or_saveexec_b64 s[8:9], s[8:9]
	v_mov_b32_e32 v0, s15
	s_xor_b64 exec, exec, s[8:9]
	s_cbranch_execz .LBB0_793
	s_lshl_b32 s14, s13, 7
	v_readlane_b32 s15, v254, 33
	s_or_b32 s14, s14, s15
	v_mov_b32_e32 v0, s14
